# GEMM phase prologues: the K-tile-1 stage loads are issued before the first wait/barrier (vmcnt(2) -> vmcnt(8)), overlapping the two exposed load latencies of a phase start
# baseline (speedup 1.0000x reference)
; #define PG8_STAGE(bufoff, gbase, voff) do { _Pragma("unroll") for (int _i = 0; _i < 2; ++_i) \
;         __builtin_amdgcn_global_load_lds((const unsigned*)((const char*)(gbase) + (voff)[_i]), (PG8_LAS unsigned*)(lds + (bufoff) + ldsw + _i * 8192), 16, 0, 0); } while (0)
; #define PG8_WAIT_V(n) asm volatile("s_waitcnt vmcnt(" #n ")" ::: "memory")
; #define PG8_BAR __builtin_amdgcn_s_barrier()
; template <class Epi, class Sched, bool ALIGN_EPI = false, bool SP2 = false>
; __device__ __forceinline__ void gemm_phase(PG8_LAS unsigned char* lds, const Gemm g, const Sched& S, const Epi& E) {
;     ...
;     for (int i = 0; i < 2; ++i) { int R, C; stage_rc(tid * 16 + i * 8192, R, C); const int Rb = Epi::PERM ? ((R & ~31) + perm32(R & 31)) : R;
;         voffA[i] = (unsigned)(R * K + C) * 2u; voffB[i] = (unsigned)(Rb * K + C) * 2u; }
;     const size_t kstep = (size_t)(BK * 2);
;     const size_t hstep = (size_t)HALF * K * 2;
;     const size_t tstep = 2 * hstep;
;     const unsigned ldsw = (unsigned)wid * 1024u;
;     const int aoff = lds_byte(wr * 64 + fr, fq * 8), boff = lds_byte(wc * 32 + fr, fq * 8);
;     ...
;         PG8_STAGE(PG8_SB(0, 0), cB, voffB); PG8_STAGE(PG8_SB(0, 1), cB + hstep, voffB); PG8_STAGE(PG8_SA(0, 0), cA, voffA); PG8_STAGE(PG8_SA(0, 1), cA + hstep, voffA);
;         if (wr == 1) PG8_BAR;
;         PG8_WAIT_V(2); PG8_BAR;
;         PG8_STAGE(PG8_SB(1, 0), cB + kstep, voffB); PG8_STAGE(PG8_SA(1, 0), cA + kstep, voffA); PG8_STAGE(PG8_SB(1, 1), cB + hstep + kstep, voffB);
;         PG8_WAIT_V(6); PG8_BAR;
.LBB0_26:
	v_bfe_u32 v18, v8, 4, 2
	v_and_b32_e32 v9, 15, v8
	v_lshlrev_b32_e32 v20, 4, v18
	v_lshlrev_b32_e32 v8, 2, v8
	v_mov_b32_e32 v149, v0
	s_and_b32 s0, s0, 3
	v_lshl_or_b32 v1, s1, 6, v9
	v_lshl_or_b32 v9, v9, 6, v20
	s_lshl_b32 s1, s1, 13
	v_and_b32_e32 v8, 32, v8
	v_lshl_add_u64 v[10:11], s[62:63], 0, v[148:149]
	v_mov_b32_e32 v145, v0
	v_bitop3_b32 v20, v9, s1, v8 bitop3:0xde
	s_lshl_b32 s1, s0, 12
	v_lshl_add_u64 v[12:13], s[62:63], 0, v[144:145]
	v_mov_b32_e32 v151, v0
	v_bitop3_b32 v143, v9, s1, v8 bitop3:0xde
	s_add_i32 m0, s5, 0x18000
	v_lshl_add_u64 v[8:9], v[10:11], 0, s[68:69]
	v_lshl_add_u64 v[14:15], s[18:19], 0, v[150:151]
	v_mov_b32_e32 v147, v0
	global_load_lds_dwordx4 v[8:9], off
	v_lshl_add_u64 v[8:9], v[12:13], 0, s[68:69]
	s_add_i32 m0, s5, 0x1a000
	s_add_i32 s1, s5, 0x8000
	s_add_i32 s60, s5, 0xa000
	v_lshl_add_u64 v[16:17], s[18:19], 0, v[146:147]
	global_load_lds_dwordx4 v[8:9], off
	v_lshl_add_u64 v[8:9], v[14:15], 0, s[68:69]
	s_mov_b32 m0, s1
	s_add_u32 s36, s62, 0x200080
	global_load_lds_dwordx4 v[8:9], off
	v_lshl_add_u64 v[8:9], v[16:17], 0, s[68:69]
	s_mov_b32 m0, s60
	s_addc_u32 s37, s63, 0
	global_load_lds_dwordx4 v[8:9], off
	s_add_i32 m0, s5, 0x1c000
	v_lshl_add_u64 v[8:9], s[36:37], 0, v[148:149]
	global_load_lds_dwordx4 v[8:9], off
	v_lshl_add_u64 v[8:9], s[36:37], 0, v[144:145]
	s_add_i32 m0, s5, 0x1e000
	v_lshlrev_b32_e32 v19, 3, v18
	global_load_lds_dwordx4 v[8:9], off
	v_lshlrev_b32_e32 v8, 17, v6
	v_and_b32_e32 v8, 0xfffc0000, v8
	v_lshl_add_u32 v5, v5, 14, v8
	v_and_b32_e32 v6, 1, v6
	v_lshl_or_b32 v5, v6, 6, v5
	v_lshl_add_u32 v152, v7, 1, v5
	v_lshlrev_b32_e32 v5, 17, v2
	v_and_b32_e32 v5, 0xfffc0000, v5
	s_waitcnt vmcnt(8)
	s_barrier
	s_waitcnt vmcnt(6)
	v_lshl_add_u32 v3, v3, 14, v5
	v_and_b32_e32 v2, 1, v2
	s_cmpk_lt_u32 s12, 0x100
	v_lshl_or_b32 v2, v2, 6, v3
	v_readlane_b32 s36, v254, 2
	v_lshl_or_b32 v162, s0, 5, v19
	s_cselect_b64 s[12:13], -1, 0
	s_mov_b32 s34, 0
	v_cmp_eq_u32_e64 s[40:41], 0, v18
	v_mov_b32_e32 v153, v0
	v_lshl_add_u32 v154, v4, 1, v2
	v_mov_b32_e32 v155, v0
	v_add_u32_e32 v163, 0, v20
	v_readlane_b32 s28, v253, 19
	s_mov_b32 s54, s36
	s_barrier
	v_readlane_b32 s37, v254, 3
	s_mov_b32 s32, 0
	s_branch .LBB0_29

; #define PG8_STAGE(bufoff, gbase, voff) do { _Pragma("unroll") for (int _i = 0; _i < 2; ++_i) \
;         __builtin_amdgcn_global_load_lds((const unsigned*)((const char*)(gbase) + (voff)[_i]), (PG8_LAS unsigned*)(lds + (bufoff) + ldsw + _i * 8192), 16, 0, 0); } while (0)
; #define PG8_WAIT_V(n) asm volatile("s_waitcnt vmcnt(" #n ")" ::: "memory")
; #define PG8_BAR __builtin_amdgcn_s_barrier()
; template <class Epi, class Sched, bool ALIGN_EPI = false, bool SP2 = false>
; __device__ __forceinline__ void gemm_phase(PG8_LAS unsigned char* lds, const Gemm g, const Sched& S, const Epi& E) {
;     ...
;     for (int i = 0; i < 2; ++i) { int R, C; stage_rc(tid * 16 + i * 8192, R, C); const int Rb = Epi::PERM ? ((R & ~31) + perm32(R & 31)) : R;
;         voffA[i] = (unsigned)(R * K + C) * 2u; voffB[i] = (unsigned)(Rb * K + C) * 2u; }
;     const size_t kstep = (size_t)(BK * 2);
;     const size_t hstep = (size_t)HALF * K * 2;
;     const size_t tstep = 2 * hstep;
;     const unsigned ldsw = (unsigned)wid * 1024u;
;     const int aoff = lds_byte(wr * 64 + fr, fq * 8), boff = lds_byte(wc * 32 + fr, fq * 8);
;     ...
;         PG8_STAGE(PG8_SB(0, 0), cB, voffB); PG8_STAGE(PG8_SB(0, 1), cB + hstep, voffB); PG8_STAGE(PG8_SA(0, 0), cA, voffA); PG8_STAGE(PG8_SA(0, 1), cA + hstep, voffA);
;         if (wr == 1) PG8_BAR;
;         PG8_WAIT_V(2); PG8_BAR;
;         PG8_STAGE(PG8_SB(1, 0), cB + kstep, voffB); PG8_STAGE(PG8_SA(1, 0), cA + kstep, voffA); PG8_STAGE(PG8_SB(1, 1), cB + hstep + kstep, voffB);
;         PG8_WAIT_V(6); PG8_BAR;
.LBB0_66:
	v_bfe_u32 v18, v16, 4, 2
	v_and_b32_e32 v17, 15, v16
	v_lshlrev_b32_e32 v19, 4, v18
	v_lshlrev_b32_e32 v16, 2, v16
	v_lshl_or_b32 v1, s19, 6, v17
	v_lshl_or_b32 v17, v17, 6, v19
	s_lshl_b32 s19, s19, 13
	v_and_b32_e32 v16, 32, v16
	s_lshl_b32 s5, s5, 5
	v_bitop3_b32 v19, v17, s19, v16 bitop3:0xde
	s_and_b32 s19, s5, 0x60
	s_lshl_b32 s5, s19, 7
	s_add_i32 m0, s62, 0x18000
	v_lshl_add_u64 v[8:9], v[8:9], 0, s[68:69]
	v_bitop3_b32 v143, v17, s5, v16 bitop3:0xde
	global_load_lds_dwordx4 v[8:9], off
	v_lshl_add_u64 v[6:7], v[6:7], 0, s[68:69]
	s_add_i32 m0, s62, 0x1a000
	s_add_i32 s5, s62, 0x8000
	s_add_i32 s57, s62, 0xa000
	global_load_lds_dwordx4 v[6:7], off
	v_lshl_add_u64 v[2:3], v[2:3], 0, s[68:69]
	s_mov_b32 m0, s5
	s_add_u32 s36, s58, 0x80080
	global_load_lds_dwordx4 v[2:3], off
	v_lshl_add_u64 v[2:3], v[4:5], 0, s[68:69]
	s_mov_b32 m0, s57
	s_addc_u32 s37, s59, 0
	global_load_lds_dwordx4 v[2:3], off
	s_add_i32 m0, s62, 0x1c000
	v_lshl_add_u64 v[2:3], s[36:37], 0, v[148:149]
	global_load_lds_dwordx4 v[2:3], off
	v_lshl_add_u64 v[2:3], s[36:37], 0, v[144:145]
	s_add_i32 m0, s62, 0x1e000
	s_cmpk_lt_u32 s18, 0x100
	global_load_lds_dwordx4 v[2:3], off
	v_lshlrev_b32_e32 v2, 5, v18
	v_mov_b32_e32 v3, v0
	v_lshl_add_u64 v[152:153], s[10:11], 0, v[2:3]
	v_lshlrev_b32_e32 v2, 15, v14
	v_and_b32_e32 v2, 0xffff0000, v2
	v_lshl_add_u32 v2, v13, 12, v2
	v_and_b32_e32 v3, 1, v14
	v_lshl_or_b32 v2, v3, 6, v2
	v_lshl_add_u32 v154, v15, 1, v2
	v_lshlrev_b32_e32 v2, 15, v10
	v_and_b32_e32 v2, 0xffff0000, v2
	s_waitcnt vmcnt(8)
	s_barrier
	s_waitcnt vmcnt(6)
	v_lshl_add_u32 v2, v11, 12, v2
	v_and_b32_e32 v3, 1, v10
	v_lshl_or_b32 v160, v18, 3, s19
	v_lshl_or_b32 v2, v3, 6, v2
	v_readlane_b32 s18, v253, 54
	s_cselect_b64 s[42:43], -1, 0
	v_mov_b32_e32 v155, v0
	v_lshl_add_u32 v156, v12, 1, v2
	v_mov_b32_e32 v157, v0
	s_mov_b32 s30, 0
	v_add_u32_e32 v161, 0, v19
	v_readlane_b32 s28, v253, 16
	s_mov_b32 s34, s18
	s_barrier
	v_readlane_b32 s19, v253, 55
	s_mov_b32 s32, 0
	s_branch .LBB0_69

; #define PG8_STAGE(bufoff, gbase, voff) do { _Pragma("unroll") for (int _i = 0; _i < 2; ++_i) \
;         __builtin_amdgcn_global_load_lds((const unsigned*)((const char*)(gbase) + (voff)[_i]), (PG8_LAS unsigned*)(lds + (bufoff) + ldsw + _i * 8192), 16, 0, 0); } while (0)
; #define PG8_WAIT_V(n) asm volatile("s_waitcnt vmcnt(" #n ")" ::: "memory")
; #define PG8_BAR __builtin_amdgcn_s_barrier()
; template <class Epi, class Sched, bool ALIGN_EPI = false, bool SP2 = false>
; __device__ __forceinline__ void gemm_phase(PG8_LAS unsigned char* lds, const Gemm g, const Sched& S, const Epi& E) {
;     ...
;     for (int i = 0; i < 2; ++i) { int R, C; stage_rc(tid * 16 + i * 8192, R, C); const int Rb = Epi::PERM ? ((R & ~31) + perm32(R & 31)) : R;
;         voffA[i] = (unsigned)(R * K + C) * 2u; voffB[i] = (unsigned)(Rb * K + C) * 2u; }
;     const size_t kstep = (size_t)(BK * 2);
;     const size_t hstep = (size_t)HALF * K * 2;
;     const size_t tstep = 2 * hstep;
;     const unsigned ldsw = (unsigned)wid * 1024u;
;     const int aoff = lds_byte(wr * 64 + fr, fq * 8), boff = lds_byte(wc * 32 + fr, fq * 8);
;     ...
;         PG8_STAGE(PG8_SB(0, 0), cB, voffB); PG8_STAGE(PG8_SB(0, 1), cB + hstep, voffB); PG8_STAGE(PG8_SA(0, 0), cA, voffA); PG8_STAGE(PG8_SA(0, 1), cA + hstep, voffA);
;         if (wr == 1) PG8_BAR;
;         PG8_WAIT_V(2); PG8_BAR;
;         PG8_STAGE(PG8_SB(1, 0), cB + kstep, voffB); PG8_STAGE(PG8_SA(1, 0), cA + kstep, voffA); PG8_STAGE(PG8_SB(1, 1), cB + hstep + kstep, voffB);
;         PG8_WAIT_V(6); PG8_BAR;
.LBB0_88:
	v_bfe_u32 v18, v8, 4, 2
	v_and_b32_e32 v9, 15, v8
	v_lshlrev_b32_e32 v20, 4, v18
	v_lshlrev_b32_e32 v8, 2, v8
	v_mov_b32_e32 v149, v0
	s_and_b32 s60, s28, 3
	v_lshl_or_b32 v1, s19, 6, v9
	v_lshl_or_b32 v9, v9, 6, v20
	s_lshl_b32 s19, s19, 13
	v_and_b32_e32 v8, 32, v8
	v_lshl_add_u64 v[10:11], s[58:59], 0, v[148:149]
	v_mov_b32_e32 v145, v0
	v_bitop3_b32 v20, v9, s19, v8 bitop3:0xde
	s_lshl_b32 s19, s60, 12
	v_lshl_add_u64 v[12:13], s[58:59], 0, v[144:145]
	v_mov_b32_e32 v151, v0
	v_bitop3_b32 v143, v9, s19, v8 bitop3:0xde
	s_add_i32 m0, s5, 0x18000
	v_lshl_add_u64 v[8:9], v[10:11], 0, s[68:69]
	v_lshl_add_u64 v[14:15], s[40:41], 0, v[150:151]
	v_mov_b32_e32 v147, v0
	global_load_lds_dwordx4 v[8:9], off
	v_lshl_add_u64 v[8:9], v[12:13], 0, s[68:69]
	s_add_i32 m0, s5, 0x1a000
	s_add_i32 s67, s5, 0x8000
	s_add_i32 s28, s5, 0xa000
	v_lshl_add_u64 v[16:17], s[40:41], 0, v[146:147]
	global_load_lds_dwordx4 v[8:9], off
	v_lshl_add_u64 v[8:9], v[14:15], 0, s[68:69]
	s_mov_b32 m0, s67
	s_add_u32 s36, s58, 0x80080
	global_load_lds_dwordx4 v[8:9], off
	v_lshl_add_u64 v[8:9], v[16:17], 0, s[68:69]
	s_mov_b32 m0, s28
	s_addc_u32 s37, s59, 0
	global_load_lds_dwordx4 v[8:9], off
	s_add_i32 m0, s5, 0x1c000
	v_lshl_add_u64 v[8:9], s[36:37], 0, v[148:149]
	global_load_lds_dwordx4 v[8:9], off
	v_lshl_add_u64 v[8:9], s[36:37], 0, v[144:145]
	s_add_i32 m0, s5, 0x1e000
	v_lshlrev_b32_e32 v19, 3, v18
	global_load_lds_dwordx4 v[8:9], off
	v_lshlrev_b32_e32 v8, 15, v6
	v_and_b32_e32 v8, 0xffff0000, v8
	v_lshl_add_u32 v5, v5, 12, v8
	v_and_b32_e32 v6, 1, v6
	v_lshl_or_b32 v5, v6, 6, v5
	v_lshl_add_u32 v152, v7, 1, v5
	v_lshlrev_b32_e32 v5, 15, v2
	v_and_b32_e32 v5, 0xffff0000, v5
	s_waitcnt vmcnt(8)
	s_barrier
	s_waitcnt vmcnt(6)
	v_lshl_add_u32 v3, v3, 12, v5
	v_and_b32_e32 v2, 1, v2
	s_cmpk_lt_u32 s18, 0x100
	v_lshl_or_b32 v2, v2, 6, v3
	v_readlane_b32 s18, v254, 2
	v_lshl_or_b32 v160, s60, 5, v19
	s_cselect_b64 s[36:37], -1, 0
	s_mov_b32 s86, 0
	v_cmp_eq_u32_e64 s[42:43], 0, v18
	v_mov_b32_e32 v153, v0
	v_lshl_add_u32 v154, v4, 1, v2
	v_mov_b32_e32 v155, v0
	v_add_u32_e32 v161, 0, v20
	v_readlane_b32 s54, v253, 19
	s_mov_b32 s73, s18
	s_barrier
	v_readlane_b32 s19, v254, 3
	s_mov_b32 s32, 0
	s_branch .LBB0_91

; #define PG8_STAGE(bufoff, gbase, voff) do { _Pragma("unroll") for (int _i = 0; _i < 2; ++_i) \
;         __builtin_amdgcn_global_load_lds((const unsigned*)((const char*)(gbase) + (voff)[_i]), (PG8_LAS unsigned*)(lds + (bufoff) + ldsw + _i * 8192), 16, 0, 0); } while (0)
; #define PG8_WAIT_V(n) asm volatile("s_waitcnt vmcnt(" #n ")" ::: "memory")
; #define PG8_BAR __builtin_amdgcn_s_barrier()
; template <class Epi, class Sched, bool ALIGN_EPI = false, bool SP2 = false>
; __device__ __forceinline__ void gemm_phase(PG8_LAS unsigned char* lds, const Gemm g, const Sched& S, const Epi& E) {
;     ...
;     for (int i = 0; i < 2; ++i) { int R, C; stage_rc(tid * 16 + i * 8192, R, C); const int Rb = Epi::PERM ? ((R & ~31) + perm32(R & 31)) : R;
;         voffA[i] = (unsigned)(R * K + C) * 2u; voffB[i] = (unsigned)(Rb * K + C) * 2u; }
;     const size_t kstep = (size_t)(BK * 2);
;     const size_t hstep = (size_t)HALF * K * 2;
;     const size_t tstep = 2 * hstep;
;     const unsigned ldsw = (unsigned)wid * 1024u;
;     const int aoff = lds_byte(wr * 64 + fr, fq * 8), boff = lds_byte(wc * 32 + fr, fq * 8);
;     ...
;         PG8_STAGE(PG8_SB(0, 0), cB, voffB); PG8_STAGE(PG8_SB(0, 1), cB + hstep, voffB); PG8_STAGE(PG8_SA(0, 0), cA, voffA); PG8_STAGE(PG8_SA(0, 1), cA + hstep, voffA);
;         if (wr == 1) PG8_BAR;
;         PG8_WAIT_V(2); PG8_BAR;
;         PG8_STAGE(PG8_SB(1, 0), cB + kstep, voffB); PG8_STAGE(PG8_SA(1, 0), cA + kstep, voffA); PG8_STAGE(PG8_SB(1, 1), cB + hstep + kstep, voffB);
;         PG8_WAIT_V(6); PG8_BAR;
.LBB0_126:
	v_and_b32_e32 v16, 15, v1
	v_and_b32_e32 v17, 48, v1
	v_lshlrev_b32_e32 v1, 2, v1
	s_and_b32 s11, s9, 3
	v_lshl_or_b32 v18, v16, 6, v17
	s_lshl_b32 s8, s8, 13
	v_and_b32_e32 v1, 32, v1
	s_add_i32 m0, s5, 0x18000
	v_lshl_add_u64 v[8:9], v[8:9], 0, s[68:69]
	v_bitop3_b32 v19, v18, s8, v1 bitop3:0xde
	s_lshl_b32 s8, s11, 12
	global_load_lds_dwordx4 v[8:9], off
	v_lshl_add_u64 v[6:7], v[6:7], 0, s[68:69]
	s_add_i32 m0, s5, 0x1a000
	s_add_i32 s54, s5, 0x8000
	s_add_i32 s57, s5, 0xa000
	v_bitop3_b32 v1, v18, s8, v1 bitop3:0xde
	global_load_lds_dwordx4 v[6:7], off
	v_lshl_add_u64 v[2:3], v[2:3], 0, s[68:69]
	s_mov_b32 m0, s54
	s_add_u32 s8, s62, 0x20080
	global_load_lds_dwordx4 v[2:3], off
	v_lshl_add_u64 v[2:3], v[4:5], 0, s[68:69]
	s_mov_b32 m0, s57
	s_addc_u32 s9, s63, 0
	global_load_lds_dwordx4 v[2:3], off
	s_add_i32 m0, s5, 0x1c000
	v_lshl_add_u64 v[2:3], s[8:9], 0, v[148:149]
	global_load_lds_dwordx4 v[2:3], off
	v_lshl_add_u64 v[2:3], s[8:9], 0, v[144:145]
	s_add_i32 m0, s5, 0x1e000
	s_cmpk_lt_u32 s10, 0x100
	global_load_lds_dwordx4 v[2:3], off
	s_cselect_b64 s[8:9], -1, 0
	s_and_b32 s10, s10, 0xffffff00
	s_lshl_b32 s11, s11, 6
	s_or_b32 s10, s11, s10
	v_or3_b32 v2, s10, v17, v16
	v_ashrrev_i32_e32 v3, 31, v2
	v_readlane_b32 s10, v254, 61
	v_lshlrev_b64 v[2:3], 4, v[2:3]
	v_readlane_b32 s11, v254, 62
	v_lshl_add_u64 v[154:155], s[6:7], 0, v[2:3]
	s_waitcnt vmcnt(8)
	s_barrier
	s_waitcnt vmcnt(6)
	v_mov_b32_e32 v157, v0
	v_lshl_add_u64 v[152:153], s[10:11], 0, v[2:3]
	v_lshlrev_b32_e32 v2, 13, v14
	v_and_b32_e32 v2, 0xffffc000, v2
	v_lshl_add_u32 v2, v13, 10, v2
	v_and_b32_e32 v3, 1, v14
	v_lshl_or_b32 v2, v3, 6, v2
	v_lshl_add_u32 v156, v15, 1, v2
	v_lshlrev_b32_e32 v2, 13, v10
	v_and_b32_e32 v2, 0xffffc000, v2
	v_lshl_add_u32 v2, v11, 10, v2
	v_and_b32_e32 v3, 1, v10
	v_lshl_or_b32 v2, v3, 6, v2
	v_readlane_b32 s10, v254, 2
	v_lshl_add_u32 v158, v12, 1, v2
	v_mov_b32_e32 v159, v0
	s_mov_b32 s60, 0
	v_add_u32_e32 v143, 0, v19
	v_readlane_b32 s86, v253, 19
	s_mov_b32 s67, s10
	s_barrier
	v_readlane_b32 s11, v254, 3
	s_mov_b32 s32, 0
	s_branch .LBB0_129

; #define PG8_STAGE(bufoff, gbase, voff) do { _Pragma("unroll") for (int _i = 0; _i < 2; ++_i) \
;         __builtin_amdgcn_global_load_lds((const unsigned*)((const char*)(gbase) + (voff)[_i]), (PG8_LAS unsigned*)(lds + (bufoff) + ldsw + _i * 8192), 16, 0, 0); } while (0)
; #define PG8_WAIT_V(n) asm volatile("s_waitcnt vmcnt(" #n ")" ::: "memory")
; #define PG8_BAR __builtin_amdgcn_s_barrier()
; template <class Epi, class Sched, bool ALIGN_EPI = false, bool SP2 = false>
; __device__ __forceinline__ void gemm_phase(PG8_LAS unsigned char* lds, const Gemm g, const Sched& S, const Epi& E) {
;     ...
;     for (int i = 0; i < 2; ++i) { int R, C; stage_rc(tid * 16 + i * 8192, R, C); const int Rb = Epi::PERM ? ((R & ~31) + perm32(R & 31)) : R;
;         voffA[i] = (unsigned)(R * K + C) * 2u; voffB[i] = (unsigned)(Rb * K + C) * 2u; }
;     const size_t kstep = (size_t)(BK * 2);
;     const size_t hstep = (size_t)HALF * K * 2;
;     const size_t tstep = 2 * hstep;
;     const unsigned ldsw = (unsigned)wid * 1024u;
;     const int aoff = lds_byte(wr * 64 + fr, fq * 8), boff = lds_byte(wc * 32 + fr, fq * 8);
;     ...
;         PG8_STAGE(PG8_SB(0, 0), cB, voffB); PG8_STAGE(PG8_SB(0, 1), cB + hstep, voffB); PG8_STAGE(PG8_SA(0, 0), cA, voffA); PG8_STAGE(PG8_SA(0, 1), cA + hstep, voffA);
;         if (wr == 1) PG8_BAR;
;         PG8_WAIT_V(2); PG8_BAR;
;         PG8_STAGE(PG8_SB(1, 0), cB + kstep, voffB); PG8_STAGE(PG8_SA(1, 0), cA + kstep, voffA); PG8_STAGE(PG8_SB(1, 1), cB + hstep + kstep, voffB);
;         PG8_WAIT_V(6); PG8_BAR;
.LBB0_146:
	v_bfe_u32 v20, v18, 4, 2
	v_and_b32_e32 v19, 15, v18
	v_lshlrev_b32_e32 v21, 3, v20
	v_lshlrev_b32_e32 v20, 4, v20
	v_lshlrev_b32_e32 v18, 2, v18
	s_and_b32 s18, s10, 3
	v_lshl_or_b32 v1, s1, 6, v19
	v_lshl_or_b32 v22, v19, 6, v20
	s_lshl_b32 s1, s1, 13
	v_and_b32_e32 v18, 32, v18
	s_add_i32 m0, s54, 0x18000
	v_lshl_add_u64 v[8:9], v[8:9], 0, s[68:69]
	v_bitop3_b32 v23, v22, s1, v18 bitop3:0xde
	s_lshl_b32 s1, s18, 12
	global_load_lds_dwordx4 v[8:9], off
	v_lshl_add_u64 v[6:7], v[6:7], 0, s[68:69]
	s_add_i32 m0, s54, 0x1a000
	s_add_i32 s62, s54, 0x8000
	s_add_i32 s63, s54, 0xa000
	global_load_lds_dwordx4 v[6:7], off
	v_lshl_add_u64 v[2:3], v[2:3], 0, s[68:69]
	s_mov_b32 m0, s62
	s_add_u32 s10, s42, 0x60080
	global_load_lds_dwordx4 v[2:3], off
	v_lshl_add_u64 v[2:3], v[4:5], 0, s[68:69]
	s_mov_b32 m0, s63
	s_addc_u32 s11, s43, 0
	global_load_lds_dwordx4 v[2:3], off
	s_add_i32 m0, s54, 0x1c000
	v_lshl_add_u64 v[2:3], s[10:11], 0, v[148:149]
	global_load_lds_dwordx4 v[2:3], off
	v_lshl_add_u64 v[2:3], s[10:11], 0, v[144:145]
	s_add_i32 m0, s54, 0x1e000
	s_cmpk_lt_u32 s0, 0x100
	global_load_lds_dwordx4 v[2:3], off
	v_bitop3_b32 v143, v22, s1, v18 bitop3:0xde
	s_cselect_b64 s[10:11], -1, 0
	s_and_b32 s0, s0, 0xffffff00
	s_lshl_b32 s1, s18, 6
	s_or_b32 s0, s1, s0
	v_or3_b32 v2, s0, v20, v19
	v_ashrrev_i32_e32 v3, 31, v2
	v_readlane_b32 s0, v254, 61
	v_lshlrev_b64 v[2:3], 4, v[2:3]
	v_readlane_b32 s1, v254, 62
	v_lshl_add_u64 v[154:155], s[6:7], 0, v[2:3]
	s_movk_i32 s6, 0x6000
	v_lshl_add_u64 v[152:153], s[0:1], 0, v[2:3]
	v_lshrrev_b32_e32 v3, 1, v15
	v_mul_lo_u32 v2, v14, s3
	v_mad_u64_u32 v[2:3], s[0:1], v3, s6, v[2:3]
	v_or_b32_e32 v2, v2, v16
	v_lshl_or_b32 v168, s18, 5, v21
	v_add_lshl_u32 v2, v2, v17, 1
	v_mov_b32_e32 v3, v0
	s_mov_b64 s[18:19], 0x60080
	v_lshl_add_u64 v[156:157], v[2:3], 0, s[18:19]
	v_lshrrev_b32_e32 v3, 1, v10
	v_mul_lo_u32 v2, v11, s3
	v_mad_u64_u32 v[2:3], s[0:1], v3, s6, v[2:3]
	s_waitcnt vmcnt(8)
	s_barrier
	s_waitcnt vmcnt(6)
	v_or_b32_e32 v2, v2, v12
	v_add_lshl_u32 v2, v2, v13, 1
	v_mov_b32_e32 v3, v0
	v_readlane_b32 s0, v254, 2
	v_lshl_add_u64 v[158:159], v[2:3], 0, s[18:19]
	s_mov_b32 s67, 0
	v_add_u32_e32 v169, 0, v23
	v_readlane_b32 s28, v253, 19
	s_mov_b32 s34, s0
	s_barrier
	v_readlane_b32 s1, v254, 3
	s_mov_b32 s32, 0
	s_branch .LBB0_149

; #define PG8_STAGE(bufoff, gbase, voff) do { _Pragma("unroll") for (int _i = 0; _i < 2; ++_i) \
;         __builtin_amdgcn_global_load_lds((const unsigned*)((const char*)(gbase) + (voff)[_i]), (PG8_LAS unsigned*)(lds + (bufoff) + ldsw + _i * 8192), 16, 0, 0); } while (0)
; #define PG8_WAIT_V(n) asm volatile("s_waitcnt vmcnt(" #n ")" ::: "memory")
; #define PG8_BAR __builtin_amdgcn_s_barrier()
; template <class Epi, class Sched, bool ALIGN_EPI = false, bool SP2 = false>
; __device__ __forceinline__ void gemm_phase(PG8_LAS unsigned char* lds, const Gemm g, const Sched& S, const Epi& E) {
;     ...
;     for (int i = 0; i < 2; ++i) { int R, C; stage_rc(tid * 16 + i * 8192, R, C); const int Rb = Epi::PERM ? ((R & ~31) + perm32(R & 31)) : R;
;         voffA[i] = (unsigned)(R * K + C) * 2u; voffB[i] = (unsigned)(Rb * K + C) * 2u; }
;     const size_t kstep = (size_t)(BK * 2);
;     const size_t hstep = (size_t)HALF * K * 2;
;     const size_t tstep = 2 * hstep;
;     const unsigned ldsw = (unsigned)wid * 1024u;
;     const int aoff = lds_byte(wr * 64 + fr, fq * 8), boff = lds_byte(wc * 32 + fr, fq * 8);
;     ...
;         PG8_STAGE(PG8_SB(0, 0), cB, voffB); PG8_STAGE(PG8_SB(0, 1), cB + hstep, voffB); PG8_STAGE(PG8_SA(0, 0), cA, voffA); PG8_STAGE(PG8_SA(0, 1), cA + hstep, voffA);
;         if (wr == 1) PG8_BAR;
;         PG8_WAIT_V(2); PG8_BAR;
;         PG8_STAGE(PG8_SB(1, 0), cB + kstep, voffB); PG8_STAGE(PG8_SA(1, 0), cA + kstep, voffA); PG8_STAGE(PG8_SB(1, 1), cB + hstep + kstep, voffB);
;         PG8_WAIT_V(6); PG8_BAR;
.LBB0_275:
	s_and_b32 s7, s5, 3
	s_add_i32 m0, s30, 0x18000
	v_lshl_add_u64 v[8:9], v[8:9], 0, s[68:69]
	s_lshl_b32 s5, s4, 13
	s_lshl_b32 s10, s7, 12
	global_load_lds_dwordx4 v[8:9], off
	v_lshl_add_u64 v[6:7], v[6:7], 0, s[68:69]
	s_add_i32 m0, s30, 0x1a000
	s_add_i32 s46, s30, 0x8000
	s_add_i32 s47, s30, 0xa000
	global_load_lds_dwordx4 v[6:7], off
	v_lshl_add_u64 v[2:3], v[2:3], 0, s[68:69]
	s_mov_b32 m0, s46
	s_add_u32 s8, s18, 0x80080
	global_load_lds_dwordx4 v[2:3], off
	v_lshl_add_u64 v[2:3], v[4:5], 0, s[68:69]
	s_mov_b32 m0, s47
	s_addc_u32 s9, s19, 0
	global_load_lds_dwordx4 v[2:3], off
	s_add_i32 m0, s30, 0x1c000
	v_lshl_add_u64 v[2:3], s[8:9], 0, v[146:147]
	global_load_lds_dwordx4 v[2:3], off
	v_lshl_add_u64 v[2:3], s[8:9], 0, v[142:143]
	s_add_i32 m0, s30, 0x1e000
	v_lshlrev_b32_e32 v6, 2, v12
	global_load_lds_dwordx4 v[2:3], off
	v_bfe_u32 v3, v12, 4, 2
	v_and_b32_e32 v2, 15, v12
	v_lshlrev_b32_e32 v4, 3, v3
	v_lshlrev_b32_e32 v3, 4, v3
	v_lshl_or_b32 v5, v2, 6, v3
	v_and_b32_e32 v6, 32, v6
	s_cmpk_lt_u32 s6, 0x100
	v_lshl_or_b32 v1, s4, 6, v2
	v_bitop3_b32 v7, v5, s5, v6 bitop3:0xde
	v_lshl_or_b32 v161, s7, 5, v4
	s_cselect_b64 s[4:5], -1, 0
	s_and_b32 s6, s6, 0xffffff00
	s_lshl_b32 s7, s7, 6
	s_or_b32 s6, s7, s6
	v_or3_b32 v2, s6, v3, v2
	v_readlane_b32 s6, v254, 61
	v_ashrrev_i32_e32 v3, 31, v2
	v_readlane_b32 s7, v254, 62
	s_waitcnt vmcnt(8)
	s_barrier
	s_waitcnt vmcnt(6)
	v_bitop3_b32 v160, v5, s10, v6 bitop3:0xde
	v_mov_b32_e32 v153, v0
	v_lshl_add_u64 v[150:151], v[2:3], 4, s[6:7]
	v_lshlrev_b32_e32 v2, 15, v15
	v_and_b32_e32 v2, 0xffff0000, v2
	v_lshl_add_u32 v2, v14, 12, v2
	v_and_b32_e32 v3, 1, v15
	v_lshl_or_b32 v2, v3, 6, v2
	v_lshl_add_u32 v152, v16, 1, v2
	v_lshlrev_b32_e32 v2, 15, v10
	v_and_b32_e32 v2, 0xffff0000, v2
	v_lshl_add_u32 v2, v11, 12, v2
	v_and_b32_e32 v3, 1, v10
	v_lshl_or_b32 v2, v3, 6, v2
	v_readlane_b32 s6, v253, 60
	v_lshl_add_u32 v154, v13, 1, v2
	v_mov_b32_e32 v155, v0
	s_mov_b32 s54, 0
	v_add_u32_e32 v162, 0, v7
	v_readlane_b32 s57, v253, 20
	s_mov_b32 s58, s6
	s_barrier
	v_readlane_b32 s7, v253, 61
	s_waitcnt vmcnt(0)
	s_mov_b32 s32, 0
	s_branch .LBB0_278
